# final candidate: nom0 + LN2 beta in LDS with plain stores + zero-C peeled first trip for every unit
# speedup vs baseline: 1.0040x; 1.0028x over previous
.LBB0_227:
	s_load_dwordx16 s[4:19], s[0:1], 0x40
	s_waitcnt lgkmcnt(0)
	v_writelane_b32 v254, s4, 37
	s_nop 1
	v_writelane_b32 v254, s5, 38
	v_writelane_b32 v254, s6, 39
	v_writelane_b32 v254, s7, 40
	v_writelane_b32 v254, s8, 41
	v_writelane_b32 v254, s9, 42
	v_writelane_b32 v254, s10, 43
	v_writelane_b32 v254, s11, 44
	v_writelane_b32 v254, s12, 45
	v_writelane_b32 v254, s13, 46
	v_writelane_b32 v254, s14, 47
	v_writelane_b32 v254, s15, 48
	v_writelane_b32 v254, s16, 49
	v_writelane_b32 v254, s17, 50
	v_writelane_b32 v254, s18, 51
	v_writelane_b32 v254, s19, 52
	s_nop 0
	v_readlane_b32 s2, v254, 15
	v_readlane_b32 s3, v254, 16
	s_mul_i32 s0, s3, 0x23f0
	s_mul_hi_u32 s1, s2, 0x23f0
	s_add_i32 s1, s1, s0
	s_mul_i32 s0, s2, 0x23f0
	s_add_u32 s0, s58, s0
	s_addc_u32 s1, s59, s1
	s_add_u32 s0, s0, 0x100000
	s_addc_u32 s1, s1, 0
	v_writelane_b32 v254, s0, 53
	s_nop 1
	v_writelane_b32 v254, s1, 54
	s_nop 0
	v_readlane_b32 s4, v254, 13
	v_readlane_b32 s5, v254, 14
	s_cmp_lt_i32 s4, 2
	s_cselect_b64 s[0:1], -1, 0
	s_cmp_gt_i32 s5, 1
	s_cselect_b64 s[2:3], -1, 0
	s_and_b64 s[0:1], s[0:1], s[2:3]
	s_andn2_b64 vcc, exec, s[0:1]
	s_cbranch_vccnz .LBB0_379
	v_readlane_b32 s12, v254, 53
	v_readlane_b32 s0, v254, 0
	v_readlane_b32 s13, v254, 54
	s_lshr_b32 s56, s0, 8
	v_mbcnt_lo_u32_b32 v2, -1, 0
	v_mbcnt_hi_u32_b32 v2, -1, v2
	s_lshl_b32 s0, s76, 5
	s_load_dwordx2 s[18:19], s[12:13], 0x30
	s_and_b32 s52, s0, 0x60
	s_lshr_b32 s0, s52, 3
	v_writelane_b32 v254, s0, 55
	s_lshl_b32 s0, s76, 10
	s_lshl_b32 s3, s56, 6
	s_lshl_b32 s95, s56, 13
	s_add_i32 s53, s0, 0
	s_waitcnt lgkmcnt(0)
	s_cmp_eq_u32 s18, 0
	s_mov_b32 s9, 0
	s_cbranch_scc1 .LBB0_247
	s_load_dwordx4 s[4:7], s[12:13], 0x0
	s_load_dwordx2 s[36:37], s[12:13], 0x10
	s_load_dwordx2 s[0:1], s[12:13], 0x3c
	s_waitcnt lgkmcnt(0)
	v_readlane_b32 s1, v254, 0
	s_andn2_b32 s1, s1, 63
	v_mbcnt_lo_u32_b32 v0, -1, 0
	v_mbcnt_hi_u32_b32 v0, -1, v0
	s_load_dwordx2 s[10:11], s[12:13], 0x28
	v_add_u32_e32 v0, s1, v0
	v_ashrrev_i32_e32 v3, 31, v0
	v_lshrrev_b32_e32 v3, 26, v3
	v_lshlrev_b32_e32 v1, 4, v0
	v_add_u32_e32 v3, v0, v3
	v_bfe_i32 v0, v0, 27, 1
	v_lshrrev_b32_e32 v0, 22, v0
	v_add_u32_e32 v0, v1, v0
	v_and_b32_e32 v0, 0xfffffc00, v0
	v_sub_u32_e32 v0, v1, v0
	v_lshrrev_b32_e32 v1, 4, v0
	v_bitop3_b32 v0, v1, v0, 32 bitop3:0x6c
	v_ashrrev_i32_e32 v4, 31, v0
	v_lshrrev_b32_e32 v4, 26, v4
	v_add_u32_e32 v4, v0, v4
	v_ashrrev_i32_e32 v5, 6, v4
	v_and_b32_e32 v4, 0xc0, v4
	v_ashrrev_i32_e32 v3, 6, v3
	v_sub_u32_e32 v0, v0, v4
	v_mov_b32_e32 v190, 1
	v_lshlrev_b32_e32 v1, 3, v3
	v_lshlrev_b32_e32 v3, 5, v3
	v_ashrrev_i16_sdwa v0, v190, sext(v0) dst_sel:DWORD dst_unused:UNUSED_PAD src0_sel:DWORD src1_sel:BYTE_0
	v_and_b32_e32 v1, -16, v1
	v_and_b32_e32 v3, 32, v3
	v_bfe_i32 v0, v0, 0, 16
	v_add_lshl_u32 v4, v3, v0, 1
	v_add_u32_e32 v3, v5, v1
	v_and_b32_e32 v6, 3, v5
	v_lshlrev_b32_e32 v0, 1, v3
	v_lshrrev_b32_e32 v1, 2, v3
	s_movk_i32 s50, 0xffe0
	s_waitcnt lgkmcnt(0)
	s_mov_b32 s8, s10
	s_mov_b32 s22, s11
	s_mov_b32 s23, s9
	v_and_b32_e32 v0, 24, v0
	v_and_b32_e32 v1, 4, v1
	v_and_or_b32 v5, v3, s50, v6
	s_lshl_b64 s[38:39], s[8:9], 6
	s_lshl_b64 s[16:17], s[22:23], 6
	v_or3_b32 v0, v5, v1, v0
	v_mad_u64_u32 v[160:161], s[12:13], v3, s10, v[4:5]
	s_add_u32 s10, s6, s16
	v_mad_u64_u32 v[0:1], s[12:13], v0, s11, v[4:5]
	s_addc_u32 s11, s7, s17
	s_add_i32 s51, s53, 0x10000
	s_mov_b32 m0, s51
	s_nop 0
	global_load_lds_dwordx4 v0, s[6:7]
	s_add_i32 s57, s53, 0x12000
	s_mov_b32 m0, s57
	s_nop 0
	global_load_lds_dwordx4 v0, s[10:11]
	s_add_u32 s10, s10, s16
	s_addc_u32 s11, s11, s17
	s_add_u32 s12, s10, s16
	s_addc_u32 s13, s11, s17
	s_add_i32 s58, s53, 0x14000
	s_mov_b32 m0, s58
	s_nop 0
	global_load_lds_dwordx4 v0, s[10:11]
	s_add_i32 s59, s53, 0x16000
	s_mov_b32 m0, s59
	s_nop 0
	global_load_lds_dwordx4 v0, s[12:13]
	s_add_u32 s14, s4, s38
	s_addc_u32 s15, s5, s39
	s_mov_b32 m0, s53
	s_nop 0
	global_load_lds_dwordx4 v160, s[4:5]
	s_add_i32 s60, s53, 0x2000
	s_mov_b32 m0, s60
	s_nop 0
	global_load_lds_dwordx4 v160, s[14:15]
	s_add_u32 s14, s14, s38
	s_addc_u32 s15, s15, s39
	s_add_u32 s24, s14, s38
	s_addc_u32 s25, s15, s39
	s_add_i32 s61, s53, 0x4000
	s_mov_b32 m0, s61
	s_nop 0
	global_load_lds_dwordx4 v160, s[14:15]
	s_add_i32 s62, s53, 0x6000
	s_mov_b32 m0, s62
	s_nop 0
	global_load_lds_dwordx4 v160, s[24:25]
	s_cmp_eq_u32 s56, 1
	s_cselect_b64 s[20:21], -1, 0
	s_cmp_lg_u32 s56, 1
	s_cbranch_scc1 .LBB0_231
	s_barrier

.LBB0_439:
	s_cmp_lt_i32 s4, 4
	s_cselect_b64 s[0:1], -1, 0
	s_cmp_gt_i32 s5, 3
	s_cselect_b64 s[2:3], -1, 0
	s_and_b64 s[0:1], s[0:1], s[2:3]
	s_andn2_b64 vcc, exec, s[0:1]
	s_cbranch_vccnz .LBB0_592
	v_readlane_b32 s4, v254, 53
	v_readlane_b32 s5, v254, 54
	v_mbcnt_lo_u32_b32 v2, -1, 0
	v_mbcnt_hi_u32_b32 v2, -1, v2
	s_load_dword s44, s[4:5], 0x1890
	s_add_u32 s0, s4, 0x1860
	v_readlane_b32 s2, v254, 0
	s_addc_u32 s1, s5, 0
	s_lshr_b32 s33, s2, 8
	s_lshl_b32 s2, s76, 5
	s_and_b32 s53, s2, 0x60
	s_lshl_b32 s4, s76, 10
	s_lshl_b32 s52, s33, 6
	s_lshl_b32 s3, s33, 13
	s_lshr_b32 s26, s53, 3
	s_add_i32 s54, s4, 0
	v_writelane_b32 v254, s2, 59
	s_waitcnt lgkmcnt(0)
	s_cmp_eq_u32 s44, 0
	s_mov_b32 s9, 0
	s_cbranch_scc1 .LBB0_459
	v_readlane_b32 s2, v254, 0
	s_load_dwordx4 s[4:7], s[0:1], 0x0
	s_load_dwordx2 s[34:35], s[0:1], 0x10
	s_load_dwordx2 s[30:31], s[0:1], 0x3c
	s_and_b32 s37, s2, 0xffffffc0
	v_mbcnt_lo_u32_b32 v0, -1, 0
	v_mbcnt_hi_u32_b32 v0, -1, v0
	s_load_dwordx2 s[10:11], s[0:1], 0x28
	v_add_u32_e32 v0, s37, v0
	v_ashrrev_i32_e32 v3, 31, v0
	v_lshrrev_b32_e32 v3, 26, v3
	v_lshlrev_b32_e32 v1, 4, v0
	v_add_u32_e32 v3, v0, v3
	v_bfe_i32 v0, v0, 27, 1
	v_lshrrev_b32_e32 v0, 22, v0
	v_add_u32_e32 v0, v1, v0
	v_and_b32_e32 v0, 0xfffffc00, v0
	v_sub_u32_e32 v0, v1, v0
	v_lshrrev_b32_e32 v1, 4, v0
	v_bitop3_b32 v0, v1, v0, 32 bitop3:0x6c
	v_ashrrev_i32_e32 v4, 31, v0
	v_lshrrev_b32_e32 v4, 26, v4
	v_add_u32_e32 v4, v0, v4
	v_ashrrev_i32_e32 v5, 6, v4
	v_and_b32_e32 v4, 0xc0, v4
	v_ashrrev_i32_e32 v3, 6, v3
	v_sub_u32_e32 v0, v0, v4
	v_mov_b32_e32 v150, 1
	v_lshlrev_b32_e32 v1, 3, v3
	v_lshlrev_b32_e32 v3, 5, v3
	v_ashrrev_i16_sdwa v0, v150, sext(v0) dst_sel:DWORD dst_unused:UNUSED_PAD src0_sel:DWORD src1_sel:BYTE_0
	v_and_b32_e32 v1, -16, v1
	v_and_b32_e32 v3, 32, v3
	v_bfe_i32 v0, v0, 0, 16
	v_add_lshl_u32 v4, v3, v0, 1
	v_add_u32_e32 v3, v5, v1
	v_and_b32_e32 v6, 3, v5
	v_lshlrev_b32_e32 v0, 1, v3
	v_lshrrev_b32_e32 v1, 2, v3
	s_movk_i32 s55, 0xffe0
	s_waitcnt lgkmcnt(0)
	s_mov_b32 s8, s10
	s_mov_b32 s20, s11
	s_mov_b32 s21, s9
	v_and_b32_e32 v0, 24, v0
	v_and_b32_e32 v1, 4, v1
	v_and_or_b32 v5, v3, s55, v6
	s_lshl_b64 s[48:49], s[8:9], 6
	s_lshl_b64 s[16:17], s[20:21], 6
	v_or3_b32 v0, v5, v1, v0
	v_mad_u64_u32 v[128:129], s[12:13], v3, s10, v[4:5]
	s_add_u32 s10, s6, s16
	v_mad_u64_u32 v[0:1], s[12:13], v0, s11, v[4:5]
	s_addc_u32 s11, s7, s17
	s_add_i32 s56, s54, 0x10000
	s_mov_b32 m0, s56
	s_nop 0
	global_load_lds_dwordx4 v0, s[6:7]
	s_add_i32 s57, s54, 0x12000
	s_mov_b32 m0, s57
	s_nop 0
	global_load_lds_dwordx4 v0, s[10:11]
	s_add_u32 s10, s10, s16
	s_addc_u32 s11, s11, s17
	s_add_u32 s12, s10, s16
	s_addc_u32 s13, s11, s17
	s_add_i32 s58, s54, 0x14000
	s_mov_b32 m0, s58
	s_nop 0
	global_load_lds_dwordx4 v0, s[10:11]
	s_add_i32 s59, s54, 0x16000
	s_mov_b32 m0, s59
	s_nop 0
	global_load_lds_dwordx4 v0, s[12:13]
	s_add_u32 s14, s4, s48
	s_addc_u32 s15, s5, s49
	s_mov_b32 m0, s54
	s_nop 0
	global_load_lds_dwordx4 v128, s[4:5]
	s_add_i32 s60, s54, 0x2000
	s_mov_b32 m0, s60
	s_nop 0
	global_load_lds_dwordx4 v128, s[14:15]
	s_add_u32 s14, s14, s48
	s_addc_u32 s15, s15, s49
	s_add_u32 s22, s14, s48
	s_addc_u32 s23, s15, s49
	s_add_i32 s61, s54, 0x4000
	s_mov_b32 m0, s61
	s_nop 0
	global_load_lds_dwordx4 v128, s[14:15]
	s_add_i32 s62, s54, 0x6000
	s_mov_b32 m0, s62
	s_nop 0
	global_load_lds_dwordx4 v128, s[22:23]
	s_cmp_eq_u32 s33, 1
	s_cselect_b64 s[18:19], -1, 0
	s_cmp_lg_u32 s33, 1
	s_cbranch_scc1 .LBB0_443
	s_barrier

.LBB0_672:
	s_cmp_lt_i32 s4, 6
	s_cselect_b64 s[0:1], -1, 0
	s_cmp_gt_i32 s5, 5
	s_cselect_b64 s[2:3], -1, 0
	s_and_b64 s[0:1], s[0:1], s[2:3]
	s_andn2_b64 vcc, exec, s[0:1]
	s_cbranch_vccnz .LBB0_772
	v_readlane_b32 s12, v254, 53
	v_readlane_b32 s13, v254, 54
	v_mbcnt_lo_u32_b32 v2, -1, 0
	v_mbcnt_hi_u32_b32 v2, -1, v2
	s_load_dwordx2 s[18:19], s[12:13], 0x9e0
	s_add_u32 s10, s12, 0x9b0
	v_readlane_b32 s0, v254, 0
	s_addc_u32 s11, s13, 0
	s_lshr_b32 s54, s0, 8
	s_lshl_b32 s0, s76, 5
	s_and_b32 s56, s0, 0x60
	s_lshl_b32 s0, s76, 10
	s_lshl_b32 s3, s54, 6
	s_lshl_b32 s50, s54, 13
	s_lshr_b32 s51, s56, 3
	s_add_i32 s57, s0, 0
	s_waitcnt lgkmcnt(0)
	s_cmp_eq_u32 s18, 0
	s_mov_b32 s9, 0
	s_cbranch_scc1 .LBB0_692
	v_readlane_b32 s2, v254, 0
	s_load_dwordx4 s[4:7], s[10:11], 0x0
	s_load_dwordx2 s[36:37], s[10:11], 0x10
	s_load_dwordx2 s[0:1], s[10:11], 0x3c
	s_and_b32 s52, s2, 0xffffffc0
	v_mbcnt_lo_u32_b32 v0, -1, 0
	v_mbcnt_hi_u32_b32 v0, -1, v0
	s_load_dwordx2 s[10:11], s[12:13], 0x9d8
	v_add_u32_e32 v0, s52, v0
	v_ashrrev_i32_e32 v3, 31, v0
	v_lshrrev_b32_e32 v3, 26, v3
	v_lshlrev_b32_e32 v1, 4, v0
	v_add_u32_e32 v3, v0, v3
	v_bfe_i32 v0, v0, 27, 1
	v_lshrrev_b32_e32 v0, 22, v0
	v_add_u32_e32 v0, v1, v0
	v_and_b32_e32 v0, 0xfffffc00, v0
	v_sub_u32_e32 v0, v1, v0
	v_lshrrev_b32_e32 v1, 4, v0
	v_bitop3_b32 v0, v1, v0, 32 bitop3:0x6c
	v_ashrrev_i32_e32 v4, 31, v0
	v_lshrrev_b32_e32 v4, 26, v4
	v_add_u32_e32 v4, v0, v4
	v_ashrrev_i32_e32 v5, 6, v4
	v_and_b32_e32 v4, 0xc0, v4
	v_ashrrev_i32_e32 v3, 6, v3
	v_sub_u32_e32 v0, v0, v4
	v_mov_b32_e32 v134, 1
	v_lshlrev_b32_e32 v1, 3, v3
	v_lshlrev_b32_e32 v3, 5, v3
	v_ashrrev_i16_sdwa v0, v134, sext(v0) dst_sel:DWORD dst_unused:UNUSED_PAD src0_sel:DWORD src1_sel:BYTE_0
	v_and_b32_e32 v1, -16, v1
	v_and_b32_e32 v3, 32, v3
	v_bfe_i32 v0, v0, 0, 16
	v_add_lshl_u32 v4, v3, v0, 1
	v_add_u32_e32 v3, v5, v1
	v_and_b32_e32 v6, 3, v5
	v_lshlrev_b32_e32 v0, 1, v3
	v_lshrrev_b32_e32 v1, 2, v3
	s_movk_i32 s53, 0xffe0
	s_waitcnt lgkmcnt(0)
	s_mov_b32 s8, s10
	s_mov_b32 s22, s11
	s_mov_b32 s23, s9
	v_and_b32_e32 v0, 24, v0
	v_and_b32_e32 v1, 4, v1
	v_and_or_b32 v5, v3, s53, v6
	s_lshl_b64 s[38:39], s[8:9], 6
	s_lshl_b64 s[16:17], s[22:23], 6
	v_or3_b32 v0, v5, v1, v0
	v_mad_u64_u32 v[128:129], s[12:13], v3, s10, v[4:5]
	s_add_u32 s10, s6, s16
	v_mad_u64_u32 v[0:1], s[12:13], v0, s11, v[4:5]
	s_addc_u32 s11, s7, s17
	s_add_i32 s55, s57, 0x10000
	s_mov_b32 m0, s55
	s_nop 0
	global_load_lds_dwordx4 v0, s[6:7]
	s_add_i32 s58, s57, 0x12000
	s_mov_b32 m0, s58
	s_nop 0
	global_load_lds_dwordx4 v0, s[10:11]
	s_add_u32 s10, s10, s16
	s_addc_u32 s11, s11, s17
	s_add_u32 s12, s10, s16
	s_addc_u32 s13, s11, s17
	s_add_i32 s2, s57, 0x14000
	s_mov_b32 m0, s2
	s_nop 0
	global_load_lds_dwordx4 v0, s[10:11]
	s_add_i32 s59, s57, 0x16000
	s_mov_b32 m0, s59
	s_nop 0
	global_load_lds_dwordx4 v0, s[12:13]
	s_add_u32 s14, s4, s38
	s_addc_u32 s15, s5, s39
	s_mov_b32 m0, s57
	s_nop 0
	global_load_lds_dwordx4 v128, s[4:5]
	s_add_i32 s60, s57, 0x2000
	s_mov_b32 m0, s60
	s_nop 0
	global_load_lds_dwordx4 v128, s[14:15]
	s_add_u32 s14, s14, s38
	s_addc_u32 s15, s15, s39
	s_add_u32 s24, s14, s38
	s_addc_u32 s25, s15, s39
	s_add_i32 s33, s57, 0x4000
	s_mov_b32 m0, s33
	s_nop 0
	global_load_lds_dwordx4 v128, s[14:15]
	s_add_i32 s61, s57, 0x6000
	s_mov_b32 m0, s61
	s_nop 0
	global_load_lds_dwordx4 v128, s[24:25]
	s_cmp_eq_u32 s54, 1
	s_cselect_b64 s[20:21], -1, 0
	s_cmp_lg_u32 s54, 1
	s_cbranch_scc1 .LBB0_676
	s_barrier

.LBB0_772:
	s_cmp_lt_i32 s4, 7
	s_cselect_b64 s[0:1], -1, 0
	s_cmp_gt_i32 s5, 6
	s_cselect_b64 s[2:3], -1, 0
	s_and_b64 s[0:1], s[0:1], s[2:3]
	s_andn2_b64 vcc, exec, s[0:1]
	s_cbranch_vccnz .LBB0_848
	v_readlane_b32 s0, v254, 53
	v_readlane_b32 s1, v254, 54
	v_mbcnt_lo_u32_b32 v2, -1, 0
	v_mbcnt_hi_u32_b32 v2, -1, v2
	s_load_dwordx4 s[24:27], s[0:1], 0xda0
	s_add_u32 s0, s0, 0xd70
	s_addc_u32 s1, s1, 0
	s_mov_b32 s17, 0
	s_waitcnt lgkmcnt(0)
	s_cmp_eq_u32 s24, 0
	s_cbranch_scc1 .LBB0_792
	v_readlane_b32 s12, v254, 0
	s_load_dwordx8 s[4:11], s[0:1], 0x0
	s_and_b32 s56, s12, 0xffffffc0
	v_mbcnt_lo_u32_b32 v0, -1, 0
	v_mbcnt_hi_u32_b32 v0, -1, v0
	s_lshr_b32 s2, s12, 8
	v_add_u32_e32 v0, s56, v0
	v_ashrrev_i32_e32 v3, 31, v0
	v_lshrrev_b32_e32 v3, 26, v3
	v_lshlrev_b32_e32 v1, 4, v0
	v_add_u32_e32 v3, v0, v3
	v_bfe_i32 v0, v0, 27, 1
	v_lshrrev_b32_e32 v0, 22, v0
	v_add_u32_e32 v0, v1, v0
	v_and_b32_e32 v0, 0xfffffc00, v0
	v_sub_u32_e32 v0, v1, v0
	v_lshrrev_b32_e32 v1, 4, v0
	v_bitop3_b32 v0, v1, v0, 32 bitop3:0x6c
	v_ashrrev_i32_e32 v4, 31, v0
	v_lshrrev_b32_e32 v4, 26, v4
	v_add_u32_e32 v4, v0, v4
	v_ashrrev_i32_e32 v5, 6, v4
	v_and_b32_e32 v4, 0xc0, v4
	v_readlane_b32 s12, v254, 53
	v_ashrrev_i32_e32 v3, 6, v3
	v_sub_u32_e32 v0, v0, v4
	v_mov_b32_e32 v136, 1
	v_readlane_b32 s13, v254, 54
	v_lshlrev_b32_e32 v1, 3, v3
	v_lshlrev_b32_e32 v3, 5, v3
	v_ashrrev_i16_sdwa v0, v136, sext(v0) dst_sel:DWORD dst_unused:UNUSED_PAD src0_sel:DWORD src1_sel:BYTE_0
	s_load_dwordx2 s[0:1], s[12:13], 0xd98
	v_and_b32_e32 v1, -16, v1
	v_and_b32_e32 v3, 32, v3
	v_bfe_i32 v0, v0, 0, 16
	v_add_lshl_u32 v4, v3, v0, 1
	v_add_u32_e32 v3, v5, v1
	v_and_b32_e32 v6, 3, v5
	v_lshlrev_b32_e32 v0, 1, v3
	v_lshrrev_b32_e32 v1, 2, v3
	s_movk_i32 s12, 0xffe0
	v_and_b32_e32 v0, 24, v0
	v_and_b32_e32 v1, 4, v1
	v_and_or_b32 v5, v3, s12, v6
	s_lshl_b32 s3, s76, 10
	v_or3_b32 v0, v5, v1, v0
	s_waitcnt lgkmcnt(0)
	s_mov_b32 s16, s0
	s_mov_b32 s20, s1
	s_mov_b32 s21, s17
	s_add_i32 s3, s3, 0
	v_mad_u64_u32 v[0:1], s[12:13], v0, s1, v[4:5]
	v_mad_u64_u32 v[128:129], s[12:13], v3, s0, v[4:5]
	s_lshl_b64 s[46:47], s[16:17], 6
	s_lshl_b64 s[0:1], s[20:21], 6
	s_add_u32 s12, s6, s0
	s_addc_u32 s13, s7, s1
	s_add_i32 s58, s3, 0x10000
	s_mov_b32 m0, s58
	s_nop 0
	global_load_lds_dwordx4 v0, s[6:7]
	s_add_i32 s59, s3, 0x12000
	s_mov_b32 m0, s59
	s_nop 0
	global_load_lds_dwordx4 v0, s[12:13]
	s_add_u32 s12, s12, s0
	s_addc_u32 s13, s13, s1
	s_add_u32 s14, s12, s0
	s_addc_u32 s15, s13, s1
	s_add_i32 s60, s3, 0x14000
	s_mov_b32 m0, s60
	s_nop 0
	global_load_lds_dwordx4 v0, s[12:13]
	s_add_i32 s61, s3, 0x16000
	s_mov_b32 m0, s61
	s_nop 0
	global_load_lds_dwordx4 v0, s[14:15]
	s_add_u32 s18, s4, s46
	s_addc_u32 s19, s5, s47
	s_mov_b32 m0, s3
	s_nop 0
	global_load_lds_dwordx4 v128, s[4:5]
	s_add_i32 s62, s3, 0x2000
	s_mov_b32 m0, s62
	s_nop 0
	global_load_lds_dwordx4 v128, s[18:19]
	s_add_u32 s18, s18, s46
	s_addc_u32 s19, s19, s47
	s_add_u32 s22, s18, s46
	s_addc_u32 s23, s19, s47
	s_add_i32 s63, s3, 0x4000
	s_mov_b32 m0, s63
	s_nop 0
	global_load_lds_dwordx4 v128, s[18:19]
	s_add_i32 s64, s3, 0x6000
	s_mov_b32 m0, s64
	s_nop 0
	global_load_lds_dwordx4 v128, s[22:23]
	s_cmp_eq_u32 s2, 1
	s_cselect_b64 s[28:29], -1, 0
	s_cmp_lg_u32 s2, 1
	s_cbranch_scc1 .LBB0_776
	s_barrier

.LBB0_912:
	s_cmp_lt_i32 s4, 9
	s_cselect_b64 s[0:1], -1, 0
	s_cmp_gt_i32 s5, 8
	s_cselect_b64 s[2:3], -1, 0
	s_and_b64 s[0:1], s[0:1], s[2:3]
	s_andn2_b64 vcc, exec, s[0:1]
	s_cbranch_vccnz .LBB0_1007
	v_readlane_b32 s12, v254, 53
	v_readlane_b32 s13, v254, 54
	s_add_u32 s10, s12, 0xeb0
	v_readlane_b32 s0, v254, 0
	s_addc_u32 s11, s13, 0
	s_lshr_b32 s48, s0, 8
	v_mbcnt_lo_u32_b32 v2, -1, 0
	v_mbcnt_hi_u32_b32 v2, -1, v2
	s_load_dwordx2 s[0:1], s[12:13], 0xee0
	s_lshl_b32 s2, s76, 5
	s_and_b32 s54, s2, 0x60
	s_lshl_b32 s2, s76, 10
	s_lshl_b32 s3, s48, 6
	s_lshl_b32 s46, s48, 13
	s_lshr_b32 s47, s54, 3
	s_add_i32 s55, s2, 0
	s_waitcnt lgkmcnt(0)
	s_cmp_eq_u32 s0, 0
	s_mov_b32 s9, 0
	s_cbranch_scc1 .LBB0_932
	v_readlane_b32 s2, v254, 0
	s_load_dwordx4 s[4:7], s[10:11], 0x0
	s_load_dwordx2 s[30:31], s[10:11], 0x10
	s_and_b32 s49, s2, 0xffffffc0
	v_mbcnt_lo_u32_b32 v0, -1, 0
	v_mbcnt_hi_u32_b32 v0, -1, v0
	s_load_dwordx2 s[10:11], s[12:13], 0xed8
	v_add_u32_e32 v0, s49, v0
	v_ashrrev_i32_e32 v3, 31, v0
	v_lshrrev_b32_e32 v3, 26, v3
	v_lshlrev_b32_e32 v1, 4, v0
	v_add_u32_e32 v3, v0, v3
	v_bfe_i32 v0, v0, 27, 1
	v_lshrrev_b32_e32 v0, 22, v0
	v_add_u32_e32 v0, v1, v0
	v_and_b32_e32 v0, 0xfffffc00, v0
	v_sub_u32_e32 v0, v1, v0
	v_lshrrev_b32_e32 v1, 4, v0
	v_bitop3_b32 v0, v1, v0, 32 bitop3:0x6c
	v_ashrrev_i32_e32 v4, 31, v0
	v_lshrrev_b32_e32 v4, 26, v4
	v_add_u32_e32 v4, v0, v4
	v_ashrrev_i32_e32 v5, 6, v4
	v_and_b32_e32 v4, 0xc0, v4
	v_ashrrev_i32_e32 v3, 6, v3
	v_sub_u32_e32 v0, v0, v4
	v_mov_b32_e32 v132, 1
	v_lshlrev_b32_e32 v1, 3, v3
	v_lshlrev_b32_e32 v3, 5, v3
	v_ashrrev_i16_sdwa v0, v132, sext(v0) dst_sel:DWORD dst_unused:UNUSED_PAD src0_sel:DWORD src1_sel:BYTE_0
	v_and_b32_e32 v1, -16, v1
	v_and_b32_e32 v3, 32, v3
	v_bfe_i32 v0, v0, 0, 16
	v_add_lshl_u32 v4, v3, v0, 1
	v_add_u32_e32 v3, v5, v1
	v_and_b32_e32 v6, 3, v5
	v_lshlrev_b32_e32 v0, 1, v3
	v_lshrrev_b32_e32 v1, 2, v3
	s_movk_i32 s50, 0xffe0
	s_waitcnt lgkmcnt(0)
	s_mov_b32 s8, s10
	s_mov_b32 s20, s11
	s_mov_b32 s21, s9
	v_and_b32_e32 v0, 24, v0
	v_and_b32_e32 v1, 4, v1
	v_and_or_b32 v5, v3, s50, v6
	s_lshl_b64 s[34:35], s[8:9], 6
	s_lshl_b64 s[16:17], s[20:21], 6
	v_or3_b32 v0, v5, v1, v0
	v_mad_u64_u32 v[128:129], s[12:13], v3, s10, v[4:5]
	s_add_u32 s10, s6, s16
	v_mad_u64_u32 v[0:1], s[12:13], v0, s11, v[4:5]
	s_addc_u32 s11, s7, s17
	s_add_i32 s51, s55, 0x10000
	s_mov_b32 m0, s51
	s_nop 0
	global_load_lds_dwordx4 v0, s[6:7]
	s_add_i32 s52, s55, 0x12000
	s_mov_b32 m0, s52
	s_nop 0
	global_load_lds_dwordx4 v0, s[10:11]
	s_add_u32 s10, s10, s16
	s_addc_u32 s11, s11, s17
	s_add_u32 s12, s10, s16
	s_addc_u32 s13, s11, s17
	s_add_i32 s53, s55, 0x14000
	s_mov_b32 m0, s53
	s_nop 0
	global_load_lds_dwordx4 v0, s[10:11]
	s_add_i32 s56, s55, 0x16000
	s_mov_b32 m0, s56
	s_nop 0
	global_load_lds_dwordx4 v0, s[12:13]
	s_add_u32 s14, s4, s34
	s_addc_u32 s15, s5, s35
	s_mov_b32 m0, s55
	s_nop 0
	global_load_lds_dwordx4 v128, s[4:5]
	s_add_i32 s57, s55, 0x2000
	s_mov_b32 m0, s57
	s_nop 0
	global_load_lds_dwordx4 v128, s[14:15]
	s_add_u32 s14, s14, s34
	s_addc_u32 s15, s15, s35
	s_add_u32 s22, s14, s34
	s_addc_u32 s23, s15, s35
	s_add_i32 s58, s55, 0x4000
	s_mov_b32 m0, s58
	s_nop 0
	global_load_lds_dwordx4 v128, s[14:15]
	s_add_i32 s59, s55, 0x6000
	s_mov_b32 m0, s59
	s_nop 0
	global_load_lds_dwordx4 v128, s[22:23]
	s_cmp_eq_u32 s48, 1
	s_cselect_b64 s[18:19], -1, 0
	s_cmp_lg_u32 s48, 1
	s_cbranch_scc1 .LBB0_916
	s_barrier

.LBB0_1007:
	s_cmp_lt_i32 s4, 10
	s_cselect_b64 s[0:1], -1, 0
	s_cmp_gt_i32 s5, 9
	s_cselect_b64 s[2:3], -1, 0
	s_and_b64 s[0:1], s[0:1], s[2:3]
	s_andn2_b64 vcc, exec, s[0:1]
	s_cbranch_vccnz .LBB0_1084
	v_readlane_b32 s0, v254, 53
	v_readlane_b32 s1, v254, 54
	v_mbcnt_lo_u32_b32 v2, -1, 0
	v_mbcnt_hi_u32_b32 v2, -1, v2
	s_load_dword s2, s[0:1], 0x1750
	s_add_u32 s26, s0, 0x1720
	s_addc_u32 s27, s1, 0
	s_mov_b32 s13, 0
	s_waitcnt lgkmcnt(0)
	s_cmp_eq_u32 s2, 0
	s_cbranch_scc1 .LBB0_1028
	v_readlane_b32 s0, v254, 0
	s_lshr_b32 s18, s0, 8
	s_load_dwordx4 s[4:7], s[26:27], 0x0
	s_load_dwordx4 s[28:31], s[26:27], 0x18
	s_load_dwordx4 s[8:11], s[26:27], 0x38
	s_andn2_b32 s0, s0, 63
	v_mbcnt_lo_u32_b32 v0, -1, 0
	v_mbcnt_hi_u32_b32 v0, -1, v0
	v_mov_b32_e32 v172, 1
	v_add_u32_e32 v0, s0, v0
	v_ashrrev_i32_e32 v3, 31, v0
	v_lshrrev_b32_e32 v3, 26, v3
	v_lshlrev_b32_e32 v1, 4, v0
	v_add_u32_e32 v3, v0, v3
	v_bfe_i32 v0, v0, 27, 1
	v_lshrrev_b32_e32 v0, 22, v0
	v_add_u32_e32 v0, v1, v0
	v_and_b32_e32 v0, 0xfffffc00, v0
	v_sub_u32_e32 v0, v1, v0
	v_lshrrev_b32_e32 v1, 4, v0
	v_bitop3_b32 v0, v1, v0, 32 bitop3:0x6c
	v_ashrrev_i32_e32 v4, 31, v0
	v_lshrrev_b32_e32 v4, 26, v4
	v_add_u32_e32 v4, v0, v4
	v_ashrrev_i32_e32 v5, 6, v4
	v_and_b32_e32 v4, 0xc0, v4
	v_ashrrev_i32_e32 v3, 6, v3
	v_sub_u32_e32 v0, v0, v4
	v_lshlrev_b32_e32 v1, 3, v3
	v_lshlrev_b32_e32 v3, 5, v3
	v_ashrrev_i16_sdwa v0, v172, sext(v0) dst_sel:DWORD dst_unused:UNUSED_PAD src0_sel:DWORD src1_sel:BYTE_0
	v_and_b32_e32 v1, -16, v1
	v_and_b32_e32 v3, 32, v3
	v_bfe_i32 v0, v0, 0, 16
	s_load_dwordx2 s[14:15], s[26:27], 0x28
	v_add_lshl_u32 v4, v3, v0, 1
	v_add_u32_e32 v3, v5, v1
	s_mov_b32 s1, s0
	v_and_b32_e32 v6, 3, v5
	v_lshlrev_b32_e32 v0, 1, v3
	v_lshrrev_b32_e32 v1, 2, v3
	s_movk_i32 s0, 0xffe0
	v_and_b32_e32 v0, 24, v0
	v_and_b32_e32 v1, 4, v1
	v_and_or_b32 v5, v3, s0, v6
	v_or3_b32 v0, v5, v1, v0
	s_waitcnt lgkmcnt(0)
	v_mad_u64_u32 v[0:1], s[16:17], v0, s15, v[4:5]
	v_mad_u64_u32 v[128:129], s[16:17], v3, s14, v[4:5]
	s_lshl_b32 s3, s76, 10
	s_mov_b32 s12, s14
	s_mov_b32 s16, s15
	s_mov_b32 s17, s13
	s_add_i32 s3, s3, 0
	s_lshl_b64 s[52:53], s[12:13], 6
	s_lshl_b64 s[34:35], s[16:17], 6
	s_add_u32 s14, s6, s34
	s_addc_u32 s15, s7, s35
	s_add_i32 s62, s3, 0x10000
	s_mov_b32 m0, s62
	s_nop 0
	global_load_lds_dwordx4 v0, s[6:7]
	s_add_i32 s63, s3, 0x12000
	s_mov_b32 m0, s63
	s_nop 0
	global_load_lds_dwordx4 v0, s[14:15]
	s_add_u32 s14, s14, s34
	s_addc_u32 s15, s15, s35
	s_add_u32 s20, s14, s34
	s_addc_u32 s21, s15, s35
	s_add_i32 s64, s3, 0x14000
	s_mov_b32 m0, s64
	s_nop 0
	global_load_lds_dwordx4 v0, s[14:15]
	s_add_i32 s65, s3, 0x16000
	s_mov_b32 m0, s65
	s_nop 0
	global_load_lds_dwordx4 v0, s[20:21]
	s_add_u32 s20, s4, s52
	s_addc_u32 s21, s5, s53
	s_mov_b32 m0, s3
	s_nop 0
	global_load_lds_dwordx4 v128, s[4:5]
	s_add_i32 s66, s3, 0x2000
	s_mov_b32 m0, s66
	s_nop 0
	global_load_lds_dwordx4 v128, s[20:21]
	s_add_u32 s20, s20, s52
	s_addc_u32 s21, s21, s53
	s_add_u32 s22, s20, s52
	s_addc_u32 s23, s21, s53
	s_add_i32 s67, s3, 0x4000
	s_add_i32 s73, s3, 0x6000
	s_mov_b32 m0, s67
	s_nop 0
	global_load_lds_dwordx4 v128, s[20:21]
	s_cmp_eq_u32 s18, 1
	s_cselect_b64 s[20:21], -1, 0
	s_mov_b32 m0, s73
	s_nop 0
	global_load_lds_dwordx4 v128, s[22:23]
	v_writelane_b32 v254, s20, 17
	s_cmp_lg_u32 s18, 1
	s_nop 0
	v_writelane_b32 v254, s21, 18
	s_cbranch_scc1 .LBB0_1011
	s_barrier

	.amdhsa_kernel _Z6mk_fwd4Args
		.amdhsa_group_segment_fixed_size 0
		.amdhsa_private_segment_fixed_size 0
		.amdhsa_kernarg_size 408
		.amdhsa_user_sgpr_count 2
		.amdhsa_user_sgpr_dispatch_ptr 0
		.amdhsa_user_sgpr_queue_ptr 0
		.amdhsa_user_sgpr_kernarg_segment_ptr 1
		.amdhsa_user_sgpr_dispatch_id 0
		.amdhsa_user_sgpr_kernarg_preload_length 0
		.amdhsa_user_sgpr_kernarg_preload_offset 0
		.amdhsa_user_sgpr_private_segment_size 0
		.amdhsa_uses_dynamic_stack 0
		.amdhsa_enable_private_segment 0
		.amdhsa_system_sgpr_workgroup_id_x 1
		.amdhsa_system_sgpr_workgroup_id_y 0
		.amdhsa_system_sgpr_workgroup_id_z 0
		.amdhsa_system_sgpr_workgroup_info 0
		.amdhsa_system_vgpr_workitem_id 0
		.amdhsa_next_free_vgpr 256
		.amdhsa_next_free_sgpr 99
		.amdhsa_accum_offset 256
		.amdhsa_reserve_vcc 1
		.amdhsa_float_round_mode_32 0
		.amdhsa_float_round_mode_16_64 0
		.amdhsa_float_denorm_mode_32 3
		.amdhsa_float_denorm_mode_16_64 3
		.amdhsa_dx10_clamp 1
		.amdhsa_ieee_mode 1
		.amdhsa_fp16_overflow 0
		.amdhsa_tg_split 0
		.amdhsa_exception_fp_ieee_invalid_op 0
		.amdhsa_exception_fp_denorm_src 0
		.amdhsa_exception_fp_ieee_div_zero 0
		.amdhsa_exception_fp_ieee_overflow 0
		.amdhsa_exception_fp_ieee_underflow 0
		.amdhsa_exception_fp_ieee_inexact 0
		.amdhsa_exception_int_div_zero 0
	.end_amdhsa_kernel

amdhsa.kernels:
  - .agpr_count:     0
    .args:
      - .offset:         0
        .size:           152
        .value_kind:     by_value
      - .offset:         152
        .size:           4
        .value_kind:     hidden_block_count_x
      - .offset:         156
        .size:           4
        .value_kind:     hidden_block_count_y
      - .offset:         160
        .size:           4
        .value_kind:     hidden_block_count_z
      - .offset:         164
        .size:           2
        .value_kind:     hidden_group_size_x
      - .offset:         166
        .size:           2
        .value_kind:     hidden_group_size_y
      - .offset:         168
        .size:           2
        .value_kind:     hidden_group_size_z
      - .offset:         170
        .size:           2
        .value_kind:     hidden_remainder_x
      - .offset:         172
        .size:           2
        .value_kind:     hidden_remainder_y
      - .offset:         174
        .size:           2
        .value_kind:     hidden_remainder_z
      - .offset:         192
        .size:           8
        .value_kind:     hidden_global_offset_x
      - .offset:         200
        .size:           8
        .value_kind:     hidden_global_offset_y
      - .offset:         208
        .size:           8
        .value_kind:     hidden_global_offset_z
      - .offset:         216
        .size:           2
        .value_kind:     hidden_grid_dims
      - .offset:         272
        .size:           4
        .value_kind:     hidden_dynamic_lds_size
    .group_segment_fixed_size: 0
    .kernarg_segment_align: 8
    .kernarg_segment_size: 408
    .language:       OpenCL C
    .language_version:
      - 2
      - 0
    .max_flat_workgroup_size: 512
    .name:           _Z6mk_fwd4Args
    .private_segment_fixed_size: 0
    .sgpr_count:     105
    .sgpr_spill_count: 99
    .symbol:         _Z6mk_fwd4Args.kd
    .uniform_work_group_size: 1
    .uses_dynamic_stack: false
    .vgpr_count:     256
    .vgpr_spill_count: 0
    .wavefront_size: 64
